# rope phase: the rotated selected-branch keys are written only to the fragment-ordered copy the attention loop reads; the in-place row-major copy (read by nothing) is no longer stored
# speedup vs baseline: 1.0036x; 1.0016x over previous
.LBB0_333:
	v_lshrrev_b32_e32 v58, 7, v26
	v_lshlrev_b32_e32 v58, 12, v58
	v_and_b32_e32 v59, 2, v26
	v_lshlrev_b32_e32 v59, 9, v59
	v_or_b32_e32 v58, v58, v59
	v_and_b32_e32 v59, 1, v26
	v_lshlrev_b32_e32 v59, 4, v59
	v_or_b32_e32 v58, v58, v59
	v_bfe_u32 v59, v26, 2, 5
	v_lshlrev_b32_e32 v59, 5, v59
	v_or_b32_e32 v58, v58, v59
	v_add_co_u32_e32 v60, vcc, v56, v58
	s_nop 1
	v_addc_co_u32_e32 v61, vcc, 0, v57, vcc
	v_ashrrev_i32_e32 v22, 2, v26
	v_ashrrev_i32_e32 v23, 31, v22
	v_lshlrev_b32_e32 v0, 3, v26
	v_and_b32_e32 v24, 24, v0
	v_lshlrev_b64 v[2:3], 8, v[22:23]
	v_lshl_add_u64 v[2:3], v[20:21], 0, v[2:3]
	v_lshlrev_b32_e32 v0, 3, v24
	v_lshl_add_u64 v[14:15], v[2:3], 0, v[0:1]
	global_load_dwordx4 v[2:5], v[14:15], off
	global_load_dwordx4 v[6:9], v[14:15], off offset:16
	global_load_dwordx4 v[10:13], v[14:15], off offset:32
	s_nop 0
	global_load_dwordx4 v[14:17], v[14:15], off offset:48
	v_mad_i64_i32 v[22:23], s[8:9], v22, s61, v[18:19]
	v_lshlrev_b32_e32 v0, 1, v24
	v_lshl_add_u64 v[22:23], v[22:23], 0, v[0:1]
	s_mov_b32 s10, 0
	s_movk_i32 s11, 0x200
	s_movk_i32 s12, 0x100
	s_waitcnt vmcnt(0) lgkmcnt(0)
	v_mov_b32_e32 v24, v15
	v_mov_b32_e32 v25, v17
	v_mov_b32_e32 v15, v16
	v_mov_b32_e32 v16, v11
	v_mov_b32_e32 v17, v13
	v_mov_b32_e32 v11, v12
	v_mov_b32_e32 v12, v7
	v_mov_b32_e32 v13, v9
	v_mov_b32_e32 v7, v8
	v_mov_b32_e32 v8, v3
	v_mov_b32_e32 v9, v5
	v_mov_b32_e32 v3, v4
	s_movk_i32 s74, 0x300
	v_lshl_add_u64 v[104:105], s[74:75], 1, v[22:23]
	global_load_dwordx4 v[64:67], v[104:105], off
	global_load_dwordx4 v[68:71], v[104:105], off offset:64
	s_movk_i32 s74, 0x340
	v_lshl_add_u64 v[106:107], s[74:75], 1, v[22:23]
	global_load_dwordx4 v[72:75], v[106:107], off
	global_load_dwordx4 v[76:79], v[106:107], off offset:64
	s_movk_i32 s74, 0x400
	v_lshl_add_u64 v[108:109], s[74:75], 1, v[22:23]
	global_load_dwordx4 v[80:83], v[108:109], off
	global_load_dwordx4 v[84:87], v[108:109], off offset:64
	s_movk_i32 s74, 0x440
	v_lshl_add_u64 v[110:111], s[74:75], 1, v[22:23]
	global_load_dwordx4 v[88:91], v[110:111], off
	global_load_dwordx4 v[92:95], v[110:111], off offset:64
	s_movk_i32 s74, 0x700
	v_lshl_add_u64 v[112:113], s[74:75], 1, v[22:23]
	global_load_dwordx4 v[96:99], v[112:113], off
	global_load_dwordx4 v[100:103], v[112:113], off offset:64
	s_waitcnt vmcnt(8)
	s_nop 1
	v_mov_b32_e32 v28, v64
	v_mov_b32_e32 v29, v65
	v_mov_b32_e32 v30, v66
	v_mov_b32_e32 v31, v67
	v_mov_b32_e32 v32, v68
	v_mov_b32_e32 v33, v69
	v_mov_b32_e32 v34, v70
	v_mov_b32_e32 v35, v71
	s_movk_i32 s74, 0x300
	s_and_b32 s98, s74, 64
	s_lshl_b32 s98, s98, 16
	v_lshl_add_u64 v[62:63], v[60:61], 0, s[98:99]
	v_lshlrev_b32_e32 v36, 16, v28
	v_lshlrev_b32_e32 v38, 16, v32
	v_and_b32_e32 v39, 0xffff0000, v32
	v_and_b32_e32 v37, 0xffff0000, v28
	v_pk_mul_f32 v[40:41], v[2:3], v[38:39]
	v_pk_mul_f32 v[38:39], v[8:9], v[38:39]
	v_lshlrev_b32_e32 v32, 16, v33
	v_and_b32_e32 v33, 0xffff0000, v33
	v_pk_fma_f32 v[40:41], v[8:9], v[36:37], v[40:41]
	v_pk_fma_f32 v[36:37], v[2:3], v[36:37], v[38:39] neg_lo:[0,0,1] neg_hi:[0,0,1]
	v_lshlrev_b32_e32 v28, 16, v29
	v_and_b32_e32 v29, 0xffff0000, v29
	v_pk_mul_f32 v[38:39], v[6:7], v[32:33]
	v_pk_mul_f32 v[32:33], v[12:13], v[32:33]
	v_lshlrev_b32_e32 v42, 16, v34
	v_and_b32_e32 v43, 0xffff0000, v34
	v_pk_fma_f32 v[38:39], v[12:13], v[28:29], v[38:39]
	v_pk_fma_f32 v[32:33], v[6:7], v[28:29], v[32:33] neg_lo:[0,0,1] neg_hi:[0,0,1]
	v_lshlrev_b32_e32 v28, 16, v30
	v_and_b32_e32 v29, 0xffff0000, v30
	v_pk_mul_f32 v[44:45], v[10:11], v[42:43]
	v_pk_mul_f32 v[42:43], v[16:17], v[42:43]
	v_pk_fma_f32 v[44:45], v[16:17], v[28:29], v[44:45]
	v_pk_fma_f32 v[42:43], v[10:11], v[28:29], v[42:43] neg_lo:[0,0,1] neg_hi:[0,0,1]
	v_lshlrev_b32_e32 v28, 16, v31
	v_and_b32_e32 v29, 0xffff0000, v31
	v_lshlrev_b32_e32 v30, 16, v35
	v_and_b32_e32 v31, 0xffff0000, v35
	v_pk_mul_f32 v[34:35], v[14:15], v[30:31]
	v_pk_mul_f32 v[30:31], v[24:25], v[30:31]
	v_pk_fma_f32 v[34:35], v[24:25], v[28:29], v[34:35]
	v_pk_fma_f32 v[46:47], v[14:15], v[28:29], v[30:31] neg_lo:[0,0,1] neg_hi:[0,0,1]
	v_cvt_pk_bf16_f32 v28, v36, v37
	v_cvt_pk_bf16_f32 v29, v32, v33
	v_cvt_pk_bf16_f32 v30, v42, v43
	v_cvt_pk_bf16_f32 v31, v46, v47
	global_store_dwordx4 v[62:63], v[28:31], off
	s_nop 1
	v_cvt_pk_bf16_f32 v28, v40, v41
	v_cvt_pk_bf16_f32 v29, v38, v39
	v_cvt_pk_bf16_f32 v30, v44, v45
	v_cvt_pk_bf16_f32 v31, v34, v35
	global_store_dwordx4 v[62:63], v[28:31], off offset:2048
	s_waitcnt vmcnt(8)
	s_nop 1
	v_mov_b32_e32 v28, v72
	v_mov_b32_e32 v29, v73
	v_mov_b32_e32 v30, v74
	v_mov_b32_e32 v31, v75
	v_mov_b32_e32 v32, v76
	v_mov_b32_e32 v33, v77
	v_mov_b32_e32 v34, v78
	v_mov_b32_e32 v35, v79
	s_movk_i32 s74, 0x340
	s_and_b32 s98, s74, 64
	s_lshl_b32 s98, s98, 16
	v_lshl_add_u64 v[62:63], v[60:61], 0, s[98:99]
	v_lshlrev_b32_e32 v36, 16, v28
	v_lshlrev_b32_e32 v38, 16, v32
	v_and_b32_e32 v39, 0xffff0000, v32
	v_and_b32_e32 v37, 0xffff0000, v28
	v_pk_mul_f32 v[40:41], v[2:3], v[38:39]
	v_pk_mul_f32 v[38:39], v[8:9], v[38:39]
	v_lshlrev_b32_e32 v32, 16, v33
	v_and_b32_e32 v33, 0xffff0000, v33
	v_pk_fma_f32 v[40:41], v[8:9], v[36:37], v[40:41]
	v_pk_fma_f32 v[36:37], v[2:3], v[36:37], v[38:39] neg_lo:[0,0,1] neg_hi:[0,0,1]
	v_lshlrev_b32_e32 v28, 16, v29
	v_and_b32_e32 v29, 0xffff0000, v29
	v_pk_mul_f32 v[38:39], v[6:7], v[32:33]
	v_pk_mul_f32 v[32:33], v[12:13], v[32:33]
	v_lshlrev_b32_e32 v42, 16, v34
	v_and_b32_e32 v43, 0xffff0000, v34
	v_pk_fma_f32 v[38:39], v[12:13], v[28:29], v[38:39]
	v_pk_fma_f32 v[32:33], v[6:7], v[28:29], v[32:33] neg_lo:[0,0,1] neg_hi:[0,0,1]
	v_lshlrev_b32_e32 v28, 16, v30
	v_and_b32_e32 v29, 0xffff0000, v30
	v_pk_mul_f32 v[44:45], v[10:11], v[42:43]
	v_pk_mul_f32 v[42:43], v[16:17], v[42:43]
	v_pk_fma_f32 v[44:45], v[16:17], v[28:29], v[44:45]
	v_pk_fma_f32 v[42:43], v[10:11], v[28:29], v[42:43] neg_lo:[0,0,1] neg_hi:[0,0,1]
	v_lshlrev_b32_e32 v28, 16, v31
	v_and_b32_e32 v29, 0xffff0000, v31
	v_lshlrev_b32_e32 v30, 16, v35
	v_and_b32_e32 v31, 0xffff0000, v35
	v_pk_mul_f32 v[34:35], v[14:15], v[30:31]
	v_pk_mul_f32 v[30:31], v[24:25], v[30:31]
	v_pk_fma_f32 v[34:35], v[24:25], v[28:29], v[34:35]
	v_pk_fma_f32 v[46:47], v[14:15], v[28:29], v[30:31] neg_lo:[0,0,1] neg_hi:[0,0,1]
	v_cvt_pk_bf16_f32 v28, v36, v37
	v_cvt_pk_bf16_f32 v29, v32, v33
	v_cvt_pk_bf16_f32 v30, v42, v43
	v_cvt_pk_bf16_f32 v31, v46, v47
	global_store_dwordx4 v[62:63], v[28:31], off
	s_nop 1
	v_cvt_pk_bf16_f32 v28, v40, v41
	v_cvt_pk_bf16_f32 v29, v38, v39
	v_cvt_pk_bf16_f32 v30, v44, v45
	v_cvt_pk_bf16_f32 v31, v34, v35
	global_store_dwordx4 v[62:63], v[28:31], off offset:2048
	s_waitcnt vmcnt(8)
	s_nop 1
	v_mov_b32_e32 v28, v80
	v_mov_b32_e32 v29, v81
	v_mov_b32_e32 v30, v82
	v_mov_b32_e32 v31, v83
	v_mov_b32_e32 v32, v84
	v_mov_b32_e32 v33, v85
	v_mov_b32_e32 v34, v86
	v_mov_b32_e32 v35, v87
	v_lshlrev_b32_e32 v36, 16, v28
	v_lshlrev_b32_e32 v38, 16, v32
	v_and_b32_e32 v39, 0xffff0000, v32
	v_and_b32_e32 v37, 0xffff0000, v28
	v_pk_mul_f32 v[40:41], v[2:3], v[38:39]
	v_pk_mul_f32 v[38:39], v[8:9], v[38:39]
	v_lshlrev_b32_e32 v32, 16, v33
	v_and_b32_e32 v33, 0xffff0000, v33
	v_pk_fma_f32 v[40:41], v[8:9], v[36:37], v[40:41]
	v_pk_fma_f32 v[36:37], v[2:3], v[36:37], v[38:39] neg_lo:[0,0,1] neg_hi:[0,0,1]
	v_lshlrev_b32_e32 v28, 16, v29
	v_and_b32_e32 v29, 0xffff0000, v29
	v_pk_mul_f32 v[38:39], v[6:7], v[32:33]
	v_pk_mul_f32 v[32:33], v[12:13], v[32:33]
	v_lshlrev_b32_e32 v42, 16, v34
	v_and_b32_e32 v43, 0xffff0000, v34
	v_pk_fma_f32 v[38:39], v[12:13], v[28:29], v[38:39]
	v_pk_fma_f32 v[32:33], v[6:7], v[28:29], v[32:33] neg_lo:[0,0,1] neg_hi:[0,0,1]
	v_lshlrev_b32_e32 v28, 16, v30
	v_and_b32_e32 v29, 0xffff0000, v30
	v_pk_mul_f32 v[44:45], v[10:11], v[42:43]
	v_pk_mul_f32 v[42:43], v[16:17], v[42:43]
	v_pk_fma_f32 v[44:45], v[16:17], v[28:29], v[44:45]
	v_pk_fma_f32 v[42:43], v[10:11], v[28:29], v[42:43] neg_lo:[0,0,1] neg_hi:[0,0,1]
	v_lshlrev_b32_e32 v28, 16, v31
	v_and_b32_e32 v29, 0xffff0000, v31
	v_lshlrev_b32_e32 v30, 16, v35
	v_and_b32_e32 v31, 0xffff0000, v35
	v_pk_mul_f32 v[34:35], v[14:15], v[30:31]
	v_pk_mul_f32 v[30:31], v[24:25], v[30:31]
	v_pk_fma_f32 v[34:35], v[24:25], v[28:29], v[34:35]
	v_pk_fma_f32 v[46:47], v[14:15], v[28:29], v[30:31] neg_lo:[0,0,1] neg_hi:[0,0,1]
	v_cvt_pk_bf16_f32 v28, v36, v37
	v_cvt_pk_bf16_f32 v29, v32, v33
	v_cvt_pk_bf16_f32 v30, v42, v43
	v_cvt_pk_bf16_f32 v31, v46, v47
	global_store_dwordx4 v[108:109], v[28:31], off
	s_nop 1
	v_cvt_pk_bf16_f32 v28, v40, v41
	v_cvt_pk_bf16_f32 v29, v38, v39
	v_cvt_pk_bf16_f32 v30, v44, v45
	v_cvt_pk_bf16_f32 v31, v34, v35
	global_store_dwordx4 v[108:109], v[28:31], off offset:64
	s_waitcnt vmcnt(8)
	s_nop 1
	v_mov_b32_e32 v28, v88
	v_mov_b32_e32 v29, v89
	v_mov_b32_e32 v30, v90
	v_mov_b32_e32 v31, v91
	v_mov_b32_e32 v32, v92
	v_mov_b32_e32 v33, v93
	v_mov_b32_e32 v34, v94
	v_mov_b32_e32 v35, v95
	v_lshlrev_b32_e32 v36, 16, v28
	v_lshlrev_b32_e32 v38, 16, v32
	v_and_b32_e32 v39, 0xffff0000, v32
	v_and_b32_e32 v37, 0xffff0000, v28
	v_pk_mul_f32 v[40:41], v[2:3], v[38:39]
	v_pk_mul_f32 v[38:39], v[8:9], v[38:39]
	v_lshlrev_b32_e32 v32, 16, v33
	v_and_b32_e32 v33, 0xffff0000, v33
	v_pk_fma_f32 v[40:41], v[8:9], v[36:37], v[40:41]
	v_pk_fma_f32 v[36:37], v[2:3], v[36:37], v[38:39] neg_lo:[0,0,1] neg_hi:[0,0,1]
	v_lshlrev_b32_e32 v28, 16, v29
	v_and_b32_e32 v29, 0xffff0000, v29
	v_pk_mul_f32 v[38:39], v[6:7], v[32:33]
	v_pk_mul_f32 v[32:33], v[12:13], v[32:33]
	v_lshlrev_b32_e32 v42, 16, v34
	v_and_b32_e32 v43, 0xffff0000, v34
	v_pk_fma_f32 v[38:39], v[12:13], v[28:29], v[38:39]
	v_pk_fma_f32 v[32:33], v[6:7], v[28:29], v[32:33] neg_lo:[0,0,1] neg_hi:[0,0,1]
	v_lshlrev_b32_e32 v28, 16, v30
	v_and_b32_e32 v29, 0xffff0000, v30
	v_pk_mul_f32 v[44:45], v[10:11], v[42:43]
	v_pk_mul_f32 v[42:43], v[16:17], v[42:43]
	v_pk_fma_f32 v[44:45], v[16:17], v[28:29], v[44:45]
	v_pk_fma_f32 v[42:43], v[10:11], v[28:29], v[42:43] neg_lo:[0,0,1] neg_hi:[0,0,1]
	v_lshlrev_b32_e32 v28, 16, v31
	v_and_b32_e32 v29, 0xffff0000, v31
	v_lshlrev_b32_e32 v30, 16, v35
	v_and_b32_e32 v31, 0xffff0000, v35
	v_pk_mul_f32 v[34:35], v[14:15], v[30:31]
	v_pk_mul_f32 v[30:31], v[24:25], v[30:31]
	v_pk_fma_f32 v[34:35], v[24:25], v[28:29], v[34:35]
	v_pk_fma_f32 v[46:47], v[14:15], v[28:29], v[30:31] neg_lo:[0,0,1] neg_hi:[0,0,1]
	v_cvt_pk_bf16_f32 v28, v36, v37
	v_cvt_pk_bf16_f32 v29, v32, v33
	v_cvt_pk_bf16_f32 v30, v42, v43
	v_cvt_pk_bf16_f32 v31, v46, v47
	global_store_dwordx4 v[110:111], v[28:31], off
	s_nop 1
	v_cvt_pk_bf16_f32 v28, v40, v41
	v_cvt_pk_bf16_f32 v29, v38, v39
	v_cvt_pk_bf16_f32 v30, v44, v45
	v_cvt_pk_bf16_f32 v31, v34, v35
	global_store_dwordx4 v[110:111], v[28:31], off offset:64
	s_waitcnt vmcnt(8)
	s_nop 1
	v_mov_b32_e32 v28, v96
	v_mov_b32_e32 v29, v97
	v_mov_b32_e32 v30, v98
	v_mov_b32_e32 v31, v99
	v_mov_b32_e32 v32, v100
	v_mov_b32_e32 v33, v101
	v_mov_b32_e32 v34, v102
	v_mov_b32_e32 v35, v103
	v_lshlrev_b32_e32 v36, 16, v28
	v_lshlrev_b32_e32 v38, 16, v32
	v_and_b32_e32 v39, 0xffff0000, v32
	v_and_b32_e32 v37, 0xffff0000, v28
	v_pk_mul_f32 v[40:41], v[2:3], v[38:39]
	v_pk_mul_f32 v[38:39], v[8:9], v[38:39]
	v_lshlrev_b32_e32 v32, 16, v33
	v_and_b32_e32 v33, 0xffff0000, v33
	v_pk_fma_f32 v[40:41], v[8:9], v[36:37], v[40:41]
	v_pk_fma_f32 v[36:37], v[2:3], v[36:37], v[38:39] neg_lo:[0,0,1] neg_hi:[0,0,1]
	v_lshlrev_b32_e32 v28, 16, v29
	v_and_b32_e32 v29, 0xffff0000, v29
	v_pk_mul_f32 v[38:39], v[6:7], v[32:33]
	v_pk_mul_f32 v[32:33], v[12:13], v[32:33]
	v_lshlrev_b32_e32 v42, 16, v34
	v_and_b32_e32 v43, 0xffff0000, v34
	v_pk_fma_f32 v[38:39], v[12:13], v[28:29], v[38:39]
	v_pk_fma_f32 v[32:33], v[6:7], v[28:29], v[32:33] neg_lo:[0,0,1] neg_hi:[0,0,1]
	v_lshlrev_b32_e32 v28, 16, v30
	v_and_b32_e32 v29, 0xffff0000, v30
	v_pk_mul_f32 v[44:45], v[10:11], v[42:43]
	v_pk_mul_f32 v[42:43], v[16:17], v[42:43]
	v_pk_fma_f32 v[44:45], v[16:17], v[28:29], v[44:45]
	v_pk_fma_f32 v[42:43], v[10:11], v[28:29], v[42:43] neg_lo:[0,0,1] neg_hi:[0,0,1]
	v_lshlrev_b32_e32 v28, 16, v31
	v_and_b32_e32 v29, 0xffff0000, v31
	v_lshlrev_b32_e32 v30, 16, v35
	v_and_b32_e32 v31, 0xffff0000, v35
	v_pk_mul_f32 v[34:35], v[14:15], v[30:31]
	v_pk_mul_f32 v[30:31], v[24:25], v[30:31]
	v_pk_fma_f32 v[34:35], v[24:25], v[28:29], v[34:35]
	v_pk_fma_f32 v[46:47], v[14:15], v[28:29], v[30:31] neg_lo:[0,0,1] neg_hi:[0,0,1]
	v_cvt_pk_bf16_f32 v28, v36, v37
	v_cvt_pk_bf16_f32 v29, v32, v33
	v_cvt_pk_bf16_f32 v30, v42, v43
	v_cvt_pk_bf16_f32 v31, v46, v47
	global_store_dwordx4 v[112:113], v[28:31], off
	s_nop 1
	v_cvt_pk_bf16_f32 v28, v40, v41
	v_cvt_pk_bf16_f32 v29, v38, v39
	v_cvt_pk_bf16_f32 v30, v44, v45
	v_cvt_pk_bf16_f32 v31, v34, v35
	global_store_dwordx4 v[112:113], v[28:31], off offset:64
	s_branch .LBB0_332
